# ma_ret: transpose-read staging plus K/V global prefetch two chunks ahead (second register set, loop unrolled x3)
# baseline (speedup 1.0000x reference)
; __device__ __forceinline__ int otid() { int t = threadIdx.x; asm volatile("" : "+v"(t)); return t; }
; __device__ __forceinline__ void ma_ret_item(const Params& p, ldsp lds, int item) {
;     const int tid = otid(), lane = tid & 63, wave = __builtin_amdgcn_readfirstlane(tid >> 6), l15 = lane & 15, q4 = lane >> 4;
;     const int es = item & 3, sc = (item >> 2) & 7, bh = item >> 5, b = bh >> 2, h = bh & 3;
;     ldsp KTt = lds; ldsp VTt = lds + 36864;
;     const bf16_t* Pb = (const bf16_t*)(p.ws + WS_P);
;     f32x4 acc[16];
; #pragma unroll
;     for (int i = 0; i < 16; ++i) acc[i] = (f32x4){0.f, 0.f, 0.f, 0.f};
;     u32x4 kr[4], vr[2];
;     { const size_t rowq = (size_t)b * 2048 + (sc * 4) * 64;
;       ld_T<256>(kr, Pb + rowq * NO + O_K + h * 256, NO, wave, lane); ld_T<128>(vr, Pb + rowq * NO + O_V + h * 512 + es * 128, NO, wave, lane); }
.LBB0_677:
	s_lshl_b32 s0, s12, 6
	v_readlane_b32 s1, v253, 36
	s_add_i32 s0, s1, s0
	s_ashr_i32 s10, s0, 5
	s_ashr_i32 s11, s10, 31
	s_lshl_b64 s[8:9], s[10:11], 11
	v_readlane_b32 s11, v253, 37
	v_mov_b32_e32 v2, v161
	s_or_b32 s8, s8, s11
	s_ashr_i32 s0, s0, 3
	v_readfirstlane_b32 s1, v2
	s_mulk_i32 s9, 0x3000
	s_mul_hi_u32 s11, s8, 0x3000
	s_ashr_i32 s1, s1, 6
	s_and_b32 s13, s0, 3
	s_add_i32 s11, s11, s9
	s_mulk_i32 s8, 0x3000
	s_add_u32 s14, s26, s8
	s_addc_u32 s11, s27, s11
	s_lshl_b32 s15, s13, 9
	s_add_u32 s8, s14, s15
	s_addc_u32 s9, s11, 0
	s_lshl_b32 s16, s1, 5
	v_and_b32_e32 v0, 31, v2
	v_and_or_b32 v29, s16, 32, v0
	v_mul_u32_u24_e32 v0, 0x1800, v29
	v_lshlrev_b32_e32 v16, 1, v0
	v_lshl_add_u64 v[0:1], s[8:9], 0, v[16:17]
	s_and_b32 s8, s1, 0x1ffffffe
	v_bfe_u32 v30, v2, 5, 1
	v_and_b32_e32 v95, 15, v2
	v_bfe_u32 v28, v2, 4, 2
	v_or_b32_e32 v2, s8, v30
	s_lshl_b32 s13, s13, 10
	v_lshlrev_b32_e32 v2, 3, v2
	s_add_u32 s8, s14, s13
	v_ashrrev_i32_e32 v3, 31, v2
	s_addc_u32 s9, s11, 0
	v_readlane_b32 s11, v255, 11
	v_lshlrev_b64 v[26:27], 1, v[2:3]
	s_add_u32 s8, s8, s11
	v_lshl_add_u64 v[0:1], v[0:1], 0, v[26:27]
	s_addc_u32 s9, s9, 0
	global_load_dwordx4 v[22:25], v[0:1], off offset:2048
	global_load_dwordx4 v[18:21], v[0:1], off offset:2176
	global_load_dwordx4 v[12:15], v[0:1], off offset:2304
	global_load_dwordx4 v[4:7], v[0:1], off offset:2432
	v_lshl_add_u64 v[0:1], s[8:9], 0, v[16:17]
	v_lshl_add_u64 v[0:1], v[0:1], 0, v[26:27]
	s_mov_b64 s[8:9], 0x1000
	v_lshl_add_u64 v[2:3], v[0:1], 0, s[8:9]
	v_add_co_u32_e32 v0, vcc, s57, v0
	s_and_b32 s8, s1, 0x3fffffe
	s_nop 0
	v_addc_co_u32_e32 v1, vcc, 0, v1, vcc
	global_load_dwordx4 v[8:11], v[0:1], off
	s_nop 0
	global_load_dwordx4 v[0:3], v[2:3], off offset:128
	v_or_b32_e32 v30, s8, v30
	s_movk_i32 s8, 0x240
	v_mul_lo_u32 v30, v30, s8
	v_or_b32_e32 v29, v29, v30
	s_lshl_b32 s8, s1, 4
	v_lshl_add_u32 v100, v29, 1, 0
	v_or_b32_e32 v29, s8, v95
	v_lshlrev_b32_e32 v94, 3, v28
	v_mul_lo_u32 v29, v29, s53
	v_or_b32_e32 v28, 32, v94
	v_mul_u32_u24_e32 v30, 0x48, v95
	v_add_lshl_u32 v31, v28, v30, 1
	v_add_lshl_u32 v32, v29, v94, 1
	v_add_lshl_u32 v33, v94, v30, 1
	v_mov_b32_e32 v29, 0x480
	v_mov_b32_e32 v30, 0x900
	v_mov_b32_e32 v36, 0xd80
	v_mov_b32_e32 v38, 0x1200
	v_mov_b32_e32 v40, 0x1680
	v_mov_b32_e32 v42, 0x1b00
	v_mov_b32_e32 v44, 0x1f80
	v_mov_b32_e32 v46, 0x2400
	v_mov_b32_e32 v48, 0x2880
	v_mov_b32_e32 v50, 0x2d00
	v_mov_b32_e32 v52, 0x3180
	v_mov_b32_e32 v54, 0x3600
	v_mov_b32_e32 v56, 0x3a80
	v_mov_b32_e32 v58, 0x3f00
	v_mov_b32_e32 v60, 0x4380
	s_mul_i32 s1, s10, 0x1800000
	v_mad_u32_u24 v29, v95, s53, v29
	v_mad_u32_u24 v30, v95, s53, v30
	v_mad_u32_u24 v36, v95, s53, v36
	v_mad_u32_u24 v38, v95, s53, v38
	v_mad_u32_u24 v40, v95, s53, v40
	v_mad_u32_u24 v42, v95, s53, v42
	v_mad_u32_u24 v44, v95, s53, v44
	v_mad_u32_u24 v46, v95, s53, v46
	v_mad_u32_u24 v48, v95, s53, v48
	v_mad_u32_u24 v50, v95, s53, v50
	v_mad_u32_u24 v52, v95, s53, v52
	v_mad_u32_u24 v54, v95, s53, v54
	v_mad_u32_u24 v56, v95, s53, v56
	v_mad_u32_u24 v58, v95, s53, v58
	v_mad_u32_u24 v60, v95, s53, v60
	s_mul_hi_i32 s11, s10, 0x1800000
	s_or_b32 s10, s1, s13
	v_add_lshl_u32 v34, v94, v29, 1
	v_add_lshl_u32 v37, v94, v36, 1
	v_add_lshl_u32 v39, v94, v38, 1
	v_add_lshl_u32 v41, v94, v40, 1
	v_add_lshl_u32 v43, v94, v42, 1
	v_add_lshl_u32 v45, v94, v44, 1
	v_add_lshl_u32 v47, v94, v46, 1
	v_add_lshl_u32 v49, v94, v48, 1
	v_add_lshl_u32 v51, v94, v50, 1
	v_add_lshl_u32 v53, v94, v52, 1
	v_add_lshl_u32 v55, v94, v54, 1
	v_add_lshl_u32 v57, v94, v56, 1
	v_add_lshl_u32 v59, v94, v58, 1
	v_add_lshl_u32 v61, v94, v60, 1
	v_add_lshl_u32 v62, v28, v29, 1
	v_add_lshl_u32 v63, v28, v30, 1
	v_add_lshl_u32 v36, v28, v36, 1
	v_add_lshl_u32 v38, v28, v38, 1
	v_add_lshl_u32 v40, v28, v40, 1
	v_add_lshl_u32 v42, v28, v42, 1
	v_add_lshl_u32 v44, v28, v44, 1
	v_add_lshl_u32 v46, v28, v46, 1
	v_add_lshl_u32 v48, v28, v48, 1
	v_add_lshl_u32 v50, v28, v50, 1
	v_add_lshl_u32 v52, v28, v52, 1
	v_add_lshl_u32 v54, v28, v54, 1
	v_add_lshl_u32 v56, v28, v56, 1
	v_add_lshl_u32 v58, v28, v58, 1
	v_add_lshl_u32 v60, v28, v60, 1
	v_lshl_add_u64 v[28:29], s[10:11], 0, v[26:27]
	s_or_b32 s10, s1, s15
	v_readlane_b32 s16, v254, 51
	v_lshl_add_u64 v[26:27], s[10:11], 0, v[26:27]
	v_readlane_b32 s10, v254, 53
	v_add_lshl_u32 v35, v94, v30, 1
	v_lshl_add_u64 v[28:29], v[28:29], 0, v[16:17]
	v_readlane_b32 s17, v254, 52
	v_lshl_add_u64 v[26:27], v[26:27], 0, v[16:17]
	v_readlane_b32 s11, v254, 54
	v_mov_b32_e32 v30, 0
	v_lshl_add_u64 v[96:97], s[16:17], 0, v[28:29]
	v_lshl_add_u64 v[98:99], s[10:11], 0, v[26:27]
	s_mov_b64 s[10:11], 0
	v_add_u32_e32 v130, 0, v32
	v_add_u32_e32 v132, 0, v33
	v_add_u32_e32 v131, 0, v34
	v_add_u32_e32 v129, 0, v35
	v_add_u32_e32 v128, 0, v37
	v_add_u32_e32 v127, 0, v39
	v_add_u32_e32 v126, 0, v41
	v_add_u32_e32 v125, 0, v43
	v_add_u32_e32 v124, 0, v45
	v_add_u32_e32 v123, 0, v47
	v_add_u32_e32 v122, 0, v49
	v_add_u32_e32 v121, 0, v51
	v_add_u32_e32 v120, 0, v53
	v_add_u32_e32 v119, 0, v55
	v_add_u32_e32 v118, 0, v57
	v_add_u32_e32 v117, 0, v59
	v_add_u32_e32 v116, 0, v61
	v_add_u32_e32 v115, 0, v31
	v_add_u32_e32 v114, 0, v62
	v_add_u32_e32 v113, 0, v63
	v_add_u32_e32 v112, 0, v36
	v_add_u32_e32 v111, 0, v38
	v_add_u32_e32 v110, 0, v40
	v_add_u32_e32 v109, 0, v42
	v_add_u32_e32 v108, 0, v44
	v_add_u32_e32 v107, 0, v46
	v_add_u32_e32 v106, 0, v48
	v_add_u32_e32 v105, 0, v50
	v_add_u32_e32 v104, 0, v52
	v_add_u32_e32 v103, 0, v54
	v_add_u32_e32 v102, 0, v56
	v_add_u32_e32 v101, 0, v58
	v_add_u32_e32 v16, 0, v60
	v_mov_b32_e32 v31, v30
	v_mov_b32_e32 v32, v30
	v_mov_b32_e32 v33, v30
	v_mov_b32_e32 v86, v30
; __device__ __forceinline__ f32x4 mma16(bf16x8 a, bf16x8 b, f32x4 c) { return __builtin_amdgcn_mfma_f32_16x16x32_bf16(a, b, c, 0, 0, 0); }
; __device__ __forceinline__ void ma_ret_item(const Params& p, ldsp lds, int item) {
;     ...
;     f32x4 acc[16];
; #pragma unroll
;     for (int i = 0; i < 16; ++i) acc[i] = (f32x4){0.f, 0.f, 0.f, 0.f};
;     u32x4 kr[4], vr[2];
;     { const size_t rowq = (size_t)b * 2048 + (sc * 4) * 64;
;       ld_T<256>(kr, Pb + rowq * NO + O_K + h * 256, NO, wave, lane); ld_T<128>(vr, Pb + rowq * NO + O_V + h * 512 + es * 128, NO, wave, lane); }
;     for (int j = 0; j < 4; ++j) { const size_t rowj = (size_t)b * 2048 + (sc * 4 + j) * 64;
;         st_T<256>(KTt, 72, kr, wave, lane); st_T<128>(VTt, 72, vr, wave, lane);
;         __syncthreads();
;         if (j < 3) { const size_t rown = rowj + 64; ld_T<256>(kr, Pb + rown * NO + O_K + h * 256, NO, wave, lane); ld_T<128>(vr, Pb + rown * NO + O_V + h * 512 + es * 128, NO, wave, lane); }
; #pragma unroll
;         for (int ks = 0; ks < 2; ++ks) { const bf16x8 bf = ldfrag(VTt, (16 * wave + l15) * 72 + 32 * ks + 8 * q4);
; #pragma unroll
;             for (int i = 0; i < 16; ++i) acc[i] = mma16(ldfrag(KTt, (16 * i + l15) * 72 + 32 * ks + 8 * q4), bf, acc[i]); }
	v_mov_b32_e32 v87, v30
	v_mov_b32_e32 v88, v30
	v_mov_b32_e32 v89, v30
	v_mov_b32_e32 v82, v30
	v_mov_b32_e32 v83, v30
	v_mov_b32_e32 v84, v30
	v_mov_b32_e32 v85, v30
	v_mov_b32_e32 v78, v30
	v_mov_b32_e32 v79, v30
	v_mov_b32_e32 v80, v30
	v_mov_b32_e32 v81, v30
	v_mov_b32_e32 v74, v30
	v_mov_b32_e32 v75, v30
	v_mov_b32_e32 v76, v30
	v_mov_b32_e32 v77, v30
	v_mov_b32_e32 v70, v30
	v_mov_b32_e32 v71, v30
	v_mov_b32_e32 v72, v30
	v_mov_b32_e32 v73, v30
	v_mov_b32_e32 v66, v30
	v_mov_b32_e32 v67, v30
	v_mov_b32_e32 v68, v30
	v_mov_b32_e32 v69, v30
	v_mov_b32_e32 v62, v30
	v_mov_b32_e32 v63, v30
	v_mov_b32_e32 v64, v30
	v_mov_b32_e32 v65, v30
	v_mov_b32_e32 v58, v30
	v_mov_b32_e32 v59, v30
	v_mov_b32_e32 v60, v30
	v_mov_b32_e32 v61, v30
	v_mov_b32_e32 v54, v30
	v_mov_b32_e32 v55, v30
	v_mov_b32_e32 v56, v30
	v_mov_b32_e32 v57, v30
	v_mov_b32_e32 v50, v30
	v_mov_b32_e32 v51, v30
	v_mov_b32_e32 v52, v30
	v_mov_b32_e32 v53, v30
	v_mov_b32_e32 v46, v30
	v_mov_b32_e32 v47, v30
	v_mov_b32_e32 v48, v30
	v_mov_b32_e32 v49, v30
	v_mov_b32_e32 v42, v30
	v_mov_b32_e32 v43, v30
	v_mov_b32_e32 v44, v30
	v_mov_b32_e32 v45, v30
	v_mov_b32_e32 v38, v30
	v_mov_b32_e32 v39, v30
	v_mov_b32_e32 v40, v30
	v_mov_b32_e32 v41, v30
	v_mov_b32_e32 v34, v30
	v_mov_b32_e32 v35, v30
	v_mov_b32_e32 v36, v30
	v_mov_b32_e32 v37, v30
	v_mov_b32_e32 v26, v30
	v_mov_b32_e32 v27, v30
	v_mov_b32_e32 v28, v30
	v_mov_b32_e32 v29, v30
	v_and_b32_e32 v176, 31, v161
	v_bfe_u32 v177, v161, 6, 1
	v_lshl_or_b32 v176, v177, 5, v176
	v_lshrrev_b32_e32 v178, 7, v161
	v_bfe_u32 v179, v161, 5, 1
	v_lshl_or_b32 v178, v178, 1, v179
	v_and_b32_e32 v179, 3, v176
	v_bfe_u32 v180, v176, 2, 2
	v_lshl_or_b32 v179, v179, 2, v180
	v_and_b32_e32 v180, 7, v179
	v_xor_b32_e32 v180, v178, v180
	v_lshrrev_b32_e32 v179, 3, v179
	v_lshlrev_b32_e32 v176, 8, v176
	v_lshl_add_u32 v176, v180, 4, v176
	v_lshl_add_u32 v172, v179, 7, v176
	v_xor_b32_e32 v173, 0x80, v172
	v_add_u32_e32 v174, 0x9000, v172
	v_add_u32_e32 v175, 0x9000, v173
	v_bfe_u32 v176, v161, 4, 2
	v_bfe_u32 v177, v161, 2, 2
	v_and_b32_e32 v178, 3, v161
	v_lshl_or_b32 v179, v176, 3, v177
	v_lshlrev_b32_e32 v180, 1, v176
	v_and_b32_e32 v180, 3, v180
	v_lshl_or_b32 v180, v177, 2, v180
	v_lshrrev_b32_e32 v177, 1, v178
	v_xor_b32_e32 v176, v177, v180
	v_and_b32_e32 v178, 1, v178
	v_lshlrev_b32_e32 v179, 8, v179
	v_lshl_add_u32 v179, v176, 4, v179
	v_lshl_add_u32 v140, v178, 3, v179
	v_xor_b32_e32 v148, 16, v140
	v_add_u32_e32 v148, 0x400, v148
	v_xor_b32_e32 v141, 32, v140
	v_xor_b32_e32 v149, 32, v148
	v_xor_b32_e32 v142, 64, v140
	v_xor_b32_e32 v150, 64, v148
	v_xor_b32_e32 v143, 0x60, v140
	v_xor_b32_e32 v151, 0x60, v148
	v_xor_b32_e32 v144, 0x80, v140
	v_xor_b32_e32 v152, 0x80, v148
	v_xor_b32_e32 v145, 0xa0, v140
	v_xor_b32_e32 v153, 0xa0, v148
	v_xor_b32_e32 v146, 0xc0, v140
	v_xor_b32_e32 v154, 0xc0, v148
	v_xor_b32_e32 v147, 0xe0, v140
	v_xor_b32_e32 v155, 0xe0, v148
	v_lshrrev_b32_e32 v176, 6, v161
	v_lshlrev_b32_e32 v176, 5, v176
	v_xor_b32_e32 v156, v176, v140
	v_xor_b32_e32 v157, v176, v148
	v_add_u32_e32 v156, 0x9000, v156
	v_add_u32_e32 v157, 0x9000, v157
	v_lshl_add_u64 v[238:239], v[98:99], 0, s[10:11]
	global_load_dwordx4 v[186:189], v[238:239], off offset:-256
	global_load_dwordx4 v[190:193], v[238:239], off offset:-128
	global_load_dwordx4 v[194:197], v[238:239], off
	global_load_dwordx4 v[206:209], v[238:239], off offset:128
	v_lshl_add_u64 v[238:239], v[96:97], 0, s[10:11]
	s_nop 0
	v_add_co_u32_e32 v238, vcc, s54, v238
	s_nop 0
	v_addc_co_u32_e32 v239, vcc, 0, v239, vcc
	s_nop 0
	global_load_dwordx4 v[230:233], v[238:239], off
	s_nop 0
	global_load_dwordx4 v[234:237], v[238:239], off offset:128
.LBB0_678:
	s_waitcnt vmcnt(11)
	ds_write_b128 v172, v[22:25]
	s_waitcnt vmcnt(10)
	ds_write_b128 v173, v[18:21]
	s_waitcnt vmcnt(9)
	ds_write_b128 v172, v[12:15] offset:16384
	s_waitcnt vmcnt(8)
	ds_write_b128 v173, v[4:7] offset:16384
	s_waitcnt vmcnt(7)
	ds_write_b128 v174, v[8:11]
	s_waitcnt vmcnt(6)
	ds_write_b128 v175, v[0:3]
	s_waitcnt lgkmcnt(0)
	s_barrier
	s_mov_b64 s[10:11], 0xc0000
	v_lshl_add_u64 v[0:1], v[98:99], 0, s[10:11]
	global_load_dwordx4 v[22:25], v[0:1], off offset:-256
	global_load_dwordx4 v[18:21], v[0:1], off offset:-128
	global_load_dwordx4 v[12:15], v[0:1], off
	global_load_dwordx4 v[4:7], v[0:1], off offset:128
	v_lshl_add_u64 v[0:1], v[96:97], 0, s[10:11]
	v_add_co_u32_e32 v0, vcc, s54, v0
	s_nop 0
	v_addc_co_u32_e32 v1, vcc, 0, v1, vcc
	global_load_dwordx4 v[8:11], v[0:1], off
	s_nop 0
	global_load_dwordx4 v[0:3], v[0:1], off offset:128
	ds_read_b64_tr_b16 v[90:91], v156
	ds_read_b64_tr_b16 v[92:93], v157
	ds_read_b64_tr_b16 v[242:243], v156 offset:8192
	ds_read_b64_tr_b16 v[244:245], v157 offset:8192
	ds_read_b64_tr_b16 v[210:211], v140
	ds_read_b64_tr_b16 v[212:213], v148
	ds_read_b64_tr_b16 v[214:215], v141
	ds_read_b64_tr_b16 v[216:217], v149
	ds_read_b64_tr_b16 v[218:219], v142
	ds_read_b64_tr_b16 v[220:221], v150
	ds_read_b64_tr_b16 v[222:223], v143
	ds_read_b64_tr_b16 v[224:225], v151
	ds_read_b64_tr_b16 v[226:227], v144
	ds_read_b64_tr_b16 v[228:229], v152
	s_waitcnt lgkmcnt(8)
	v_mfma_f32_16x16x32_bf16 v[26:29], v[210:213], v[90:93], v[26:29]
	ds_read_b64_tr_b16 v[210:211], v145
	ds_read_b64_tr_b16 v[212:213], v153
	s_waitcnt lgkmcnt(8)
	v_mfma_f32_16x16x32_bf16 v[34:37], v[214:217], v[90:93], v[34:37]
	ds_read_b64_tr_b16 v[214:215], v146
	ds_read_b64_tr_b16 v[216:217], v154
	s_waitcnt lgkmcnt(8)
	v_mfma_f32_16x16x32_bf16 v[38:41], v[218:221], v[90:93], v[38:41]
	ds_read_b64_tr_b16 v[218:219], v147
	ds_read_b64_tr_b16 v[220:221], v155
	s_waitcnt lgkmcnt(8)
; __device__ __forceinline__ f32x4 mma16(bf16x8 a, bf16x8 b, f32x4 c) { return __builtin_amdgcn_mfma_f32_16x16x32_bf16(a, b, c, 0, 0, 0); }
; __device__ __forceinline__ void ma_ret_item(const Params& p, ldsp lds, int item) {
;     ...
;     for (int j = 0; j < 4; ++j) { const size_t rowj = (size_t)b * 2048 + (sc * 4 + j) * 64;
;         st_T<256>(KTt, 72, kr, wave, lane); st_T<128>(VTt, 72, vr, wave, lane);
;         __syncthreads();
;         if (j < 3) { const size_t rown = rowj + 64; ld_T<256>(kr, Pb + rown * NO + O_K + h * 256, NO, wave, lane); ld_T<128>(vr, Pb + rown * NO + O_V + h * 512 + es * 128, NO, wave, lane); }
; #pragma unroll
;         for (int ks = 0; ks < 2; ++ks) { const bf16x8 bf = ldfrag(VTt, (16 * wave + l15) * 72 + 32 * ks + 8 * q4);
; #pragma unroll
;             for (int i = 0; i < 16; ++i) acc[i] = mma16(ldfrag(KTt, (16 * i + l15) * 72 + 32 * ks + 8 * q4), bf, acc[i]); }
;         __syncthreads(); }
	v_mfma_f32_16x16x32_bf16 v[42:45], v[222:225], v[90:93], v[42:45]
	ds_read_b64_tr_b16 v[222:223], v140 offset:16384
	ds_read_b64_tr_b16 v[224:225], v148 offset:16384
	s_waitcnt lgkmcnt(8)
	v_mfma_f32_16x16x32_bf16 v[46:49], v[226:229], v[90:93], v[46:49]
	ds_read_b64_tr_b16 v[226:227], v141 offset:16384
	ds_read_b64_tr_b16 v[228:229], v149 offset:16384
	s_waitcnt lgkmcnt(8)
	v_mfma_f32_16x16x32_bf16 v[50:53], v[210:213], v[90:93], v[50:53]
	ds_read_b64_tr_b16 v[210:211], v142 offset:16384
	ds_read_b64_tr_b16 v[212:213], v150 offset:16384
	s_waitcnt lgkmcnt(8)
	v_mfma_f32_16x16x32_bf16 v[54:57], v[214:217], v[90:93], v[54:57]
	ds_read_b64_tr_b16 v[214:215], v143 offset:16384
	ds_read_b64_tr_b16 v[216:217], v151 offset:16384
	s_waitcnt lgkmcnt(8)
	v_mfma_f32_16x16x32_bf16 v[58:61], v[218:221], v[90:93], v[58:61]
	ds_read_b64_tr_b16 v[218:219], v144 offset:16384
	ds_read_b64_tr_b16 v[220:221], v152 offset:16384
	s_waitcnt lgkmcnt(8)
	v_mfma_f32_16x16x32_bf16 v[62:65], v[222:225], v[90:93], v[62:65]
	ds_read_b64_tr_b16 v[222:223], v145 offset:16384
	ds_read_b64_tr_b16 v[224:225], v153 offset:16384
	s_waitcnt lgkmcnt(8)
	v_mfma_f32_16x16x32_bf16 v[66:69], v[226:229], v[90:93], v[66:69]
	ds_read_b64_tr_b16 v[226:227], v146 offset:16384
	ds_read_b64_tr_b16 v[228:229], v154 offset:16384
	s_waitcnt lgkmcnt(8)
	v_mfma_f32_16x16x32_bf16 v[70:73], v[210:213], v[90:93], v[70:73]
	ds_read_b64_tr_b16 v[210:211], v147 offset:16384
	ds_read_b64_tr_b16 v[212:213], v155 offset:16384
	s_waitcnt lgkmcnt(8)
	v_mfma_f32_16x16x32_bf16 v[74:77], v[214:217], v[90:93], v[74:77]
	ds_read_b64_tr_b16 v[214:215], v140 offset:8192
	ds_read_b64_tr_b16 v[216:217], v148 offset:8192
	s_waitcnt lgkmcnt(8)
	v_mfma_f32_16x16x32_bf16 v[78:81], v[218:221], v[90:93], v[78:81]
	ds_read_b64_tr_b16 v[218:219], v141 offset:8192
	ds_read_b64_tr_b16 v[220:221], v149 offset:8192
	s_waitcnt lgkmcnt(8)
	v_mfma_f32_16x16x32_bf16 v[82:85], v[222:225], v[90:93], v[82:85]
	ds_read_b64_tr_b16 v[222:223], v142 offset:8192
	ds_read_b64_tr_b16 v[224:225], v150 offset:8192
	s_waitcnt lgkmcnt(8)
	v_mfma_f32_16x16x32_bf16 v[86:89], v[226:229], v[90:93], v[86:89]
	ds_read_b64_tr_b16 v[226:227], v143 offset:8192
	ds_read_b64_tr_b16 v[228:229], v151 offset:8192
	s_waitcnt lgkmcnt(8)
	v_mfma_f32_16x16x32_bf16 v[30:33], v[210:213], v[90:93], v[30:33]
	ds_read_b64_tr_b16 v[210:211], v144 offset:8192
	ds_read_b64_tr_b16 v[212:213], v152 offset:8192
	s_waitcnt lgkmcnt(8)
	v_mfma_f32_16x16x32_bf16 v[26:29], v[214:217], v[242:245], v[26:29]
	ds_read_b64_tr_b16 v[214:215], v145 offset:8192
	ds_read_b64_tr_b16 v[216:217], v153 offset:8192
	s_waitcnt lgkmcnt(8)
	v_mfma_f32_16x16x32_bf16 v[34:37], v[218:221], v[242:245], v[34:37]
	ds_read_b64_tr_b16 v[218:219], v146 offset:8192
	ds_read_b64_tr_b16 v[220:221], v154 offset:8192
	s_waitcnt lgkmcnt(8)
	v_mfma_f32_16x16x32_bf16 v[38:41], v[222:225], v[242:245], v[38:41]
	ds_read_b64_tr_b16 v[222:223], v147 offset:8192
	ds_read_b64_tr_b16 v[224:225], v155 offset:8192
	s_waitcnt lgkmcnt(8)
	v_mfma_f32_16x16x32_bf16 v[42:45], v[226:229], v[242:245], v[42:45]
	ds_read_b64_tr_b16 v[226:227], v140 offset:24576
	ds_read_b64_tr_b16 v[228:229], v148 offset:24576
	s_waitcnt lgkmcnt(8)
	v_mfma_f32_16x16x32_bf16 v[46:49], v[210:213], v[242:245], v[46:49]
	ds_read_b64_tr_b16 v[210:211], v141 offset:24576
	ds_read_b64_tr_b16 v[212:213], v149 offset:24576
	s_waitcnt lgkmcnt(8)
	v_mfma_f32_16x16x32_bf16 v[50:53], v[214:217], v[242:245], v[50:53]
	ds_read_b64_tr_b16 v[214:215], v142 offset:24576
	ds_read_b64_tr_b16 v[216:217], v150 offset:24576
	s_waitcnt lgkmcnt(8)
	v_mfma_f32_16x16x32_bf16 v[54:57], v[218:221], v[242:245], v[54:57]
	ds_read_b64_tr_b16 v[218:219], v143 offset:24576
	ds_read_b64_tr_b16 v[220:221], v151 offset:24576
	s_waitcnt lgkmcnt(8)
	v_mfma_f32_16x16x32_bf16 v[58:61], v[222:225], v[242:245], v[58:61]
	ds_read_b64_tr_b16 v[222:223], v144 offset:24576
	ds_read_b64_tr_b16 v[224:225], v152 offset:24576
	s_waitcnt lgkmcnt(8)
	v_mfma_f32_16x16x32_bf16 v[62:65], v[226:229], v[242:245], v[62:65]
	ds_read_b64_tr_b16 v[226:227], v145 offset:24576
	ds_read_b64_tr_b16 v[228:229], v153 offset:24576
	s_waitcnt lgkmcnt(8)
	v_mfma_f32_16x16x32_bf16 v[66:69], v[210:213], v[242:245], v[66:69]
	ds_read_b64_tr_b16 v[210:211], v146 offset:24576
	ds_read_b64_tr_b16 v[212:213], v154 offset:24576
	s_waitcnt lgkmcnt(8)
	v_mfma_f32_16x16x32_bf16 v[70:73], v[214:217], v[242:245], v[70:73]
	ds_read_b64_tr_b16 v[214:215], v147 offset:24576
	ds_read_b64_tr_b16 v[216:217], v155 offset:24576
	s_waitcnt lgkmcnt(8)
	v_mfma_f32_16x16x32_bf16 v[74:77], v[218:221], v[242:245], v[74:77]
	s_waitcnt lgkmcnt(6)
	v_mfma_f32_16x16x32_bf16 v[78:81], v[222:225], v[242:245], v[78:81]
	s_waitcnt lgkmcnt(4)
	v_mfma_f32_16x16x32_bf16 v[82:85], v[226:229], v[242:245], v[82:85]
	s_waitcnt lgkmcnt(2)
	v_mfma_f32_16x16x32_bf16 v[86:89], v[210:213], v[242:245], v[86:89]
	s_waitcnt lgkmcnt(0)
	s_barrier
	v_mfma_f32_16x16x32_bf16 v[30:33], v[214:217], v[242:245], v[30:33]
	s_waitcnt vmcnt(11)
	ds_write_b128 v172, v[186:189]
	s_waitcnt vmcnt(10)
	ds_write_b128 v173, v[190:193]
	s_waitcnt vmcnt(9)
	ds_write_b128 v172, v[194:197] offset:16384
	s_waitcnt vmcnt(8)
	ds_write_b128 v173, v[206:209] offset:16384
	s_waitcnt vmcnt(7)
	ds_write_b128 v174, v[230:233]
	s_waitcnt vmcnt(6)
	ds_write_b128 v175, v[234:237]
	s_waitcnt lgkmcnt(0)
	s_barrier
; __device__ __forceinline__ f32x4 mma16(bf16x8 a, bf16x8 b, f32x4 c) { return __builtin_amdgcn_mfma_f32_16x16x32_bf16(a, b, c, 0, 0, 0); }
; __device__ __forceinline__ void ma_ret_item(const Params& p, ldsp lds, int item) {
;     ...
;     for (int j = 0; j < 4; ++j) { const size_t rowj = (size_t)b * 2048 + (sc * 4 + j) * 64;
;         st_T<256>(KTt, 72, kr, wave, lane); st_T<128>(VTt, 72, vr, wave, lane);
;         __syncthreads();
;         if (j < 3) { const size_t rown = rowj + 64; ld_T<256>(kr, Pb + rown * NO + O_K + h * 256, NO, wave, lane); ld_T<128>(vr, Pb + rown * NO + O_V + h * 512 + es * 128, NO, wave, lane); }
; #pragma unroll
;         for (int ks = 0; ks < 2; ++ks) { const bf16x8 bf = ldfrag(VTt, (16 * wave + l15) * 72 + 32 * ks + 8 * q4);
; #pragma unroll
;             for (int i = 0; i < 16; ++i) acc[i] = mma16(ldfrag(KTt, (16 * i + l15) * 72 + 32 * ks + 8 * q4), bf, acc[i]); }
	s_mov_b64 s[10:11], 0x180000
	v_lshl_add_u64 v[238:239], v[98:99], 0, s[10:11]
	global_load_dwordx4 v[186:189], v[238:239], off offset:-256
	global_load_dwordx4 v[190:193], v[238:239], off offset:-128
	global_load_dwordx4 v[194:197], v[238:239], off
	global_load_dwordx4 v[206:209], v[238:239], off offset:128
	v_lshl_add_u64 v[238:239], v[96:97], 0, s[10:11]
	s_nop 0
	v_add_co_u32_e32 v238, vcc, s54, v238
	s_nop 0
	v_addc_co_u32_e32 v239, vcc, 0, v239, vcc
	s_nop 0
	global_load_dwordx4 v[230:233], v[238:239], off
	s_nop 0
	global_load_dwordx4 v[234:237], v[238:239], off offset:128
	ds_read_b64_tr_b16 v[90:91], v156
	ds_read_b64_tr_b16 v[92:93], v157
	ds_read_b64_tr_b16 v[242:243], v156 offset:8192
	ds_read_b64_tr_b16 v[244:245], v157 offset:8192
	ds_read_b64_tr_b16 v[210:211], v140
	ds_read_b64_tr_b16 v[212:213], v148
	ds_read_b64_tr_b16 v[214:215], v141
	ds_read_b64_tr_b16 v[216:217], v149
	ds_read_b64_tr_b16 v[218:219], v142
	ds_read_b64_tr_b16 v[220:221], v150
	ds_read_b64_tr_b16 v[222:223], v143
	ds_read_b64_tr_b16 v[224:225], v151
	ds_read_b64_tr_b16 v[226:227], v144
	ds_read_b64_tr_b16 v[228:229], v152
	s_waitcnt lgkmcnt(8)
	v_mfma_f32_16x16x32_bf16 v[26:29], v[210:213], v[90:93], v[26:29]
	ds_read_b64_tr_b16 v[210:211], v145
	ds_read_b64_tr_b16 v[212:213], v153
	s_waitcnt lgkmcnt(8)
	v_mfma_f32_16x16x32_bf16 v[34:37], v[214:217], v[90:93], v[34:37]
	ds_read_b64_tr_b16 v[214:215], v146
	ds_read_b64_tr_b16 v[216:217], v154
	s_waitcnt lgkmcnt(8)
	v_mfma_f32_16x16x32_bf16 v[38:41], v[218:221], v[90:93], v[38:41]
	ds_read_b64_tr_b16 v[218:219], v147
	ds_read_b64_tr_b16 v[220:221], v155
	s_waitcnt lgkmcnt(8)
	v_mfma_f32_16x16x32_bf16 v[42:45], v[222:225], v[90:93], v[42:45]
	ds_read_b64_tr_b16 v[222:223], v140 offset:16384
	ds_read_b64_tr_b16 v[224:225], v148 offset:16384
	s_waitcnt lgkmcnt(8)
	v_mfma_f32_16x16x32_bf16 v[46:49], v[226:229], v[90:93], v[46:49]
	ds_read_b64_tr_b16 v[226:227], v141 offset:16384
	ds_read_b64_tr_b16 v[228:229], v149 offset:16384
	s_waitcnt lgkmcnt(8)
	v_mfma_f32_16x16x32_bf16 v[50:53], v[210:213], v[90:93], v[50:53]
	ds_read_b64_tr_b16 v[210:211], v142 offset:16384
	ds_read_b64_tr_b16 v[212:213], v150 offset:16384
	s_waitcnt lgkmcnt(8)
	v_mfma_f32_16x16x32_bf16 v[54:57], v[214:217], v[90:93], v[54:57]
	ds_read_b64_tr_b16 v[214:215], v143 offset:16384
	ds_read_b64_tr_b16 v[216:217], v151 offset:16384
	s_waitcnt lgkmcnt(8)
	v_mfma_f32_16x16x32_bf16 v[58:61], v[218:221], v[90:93], v[58:61]
	ds_read_b64_tr_b16 v[218:219], v144 offset:16384
	ds_read_b64_tr_b16 v[220:221], v152 offset:16384
	s_waitcnt lgkmcnt(8)
	v_mfma_f32_16x16x32_bf16 v[62:65], v[222:225], v[90:93], v[62:65]
	ds_read_b64_tr_b16 v[222:223], v145 offset:16384
	ds_read_b64_tr_b16 v[224:225], v153 offset:16384
	s_waitcnt lgkmcnt(8)
	v_mfma_f32_16x16x32_bf16 v[66:69], v[226:229], v[90:93], v[66:69]
	ds_read_b64_tr_b16 v[226:227], v146 offset:16384
	ds_read_b64_tr_b16 v[228:229], v154 offset:16384
	s_waitcnt lgkmcnt(8)
	v_mfma_f32_16x16x32_bf16 v[70:73], v[210:213], v[90:93], v[70:73]
	ds_read_b64_tr_b16 v[210:211], v147 offset:16384
	ds_read_b64_tr_b16 v[212:213], v155 offset:16384
	s_waitcnt lgkmcnt(8)
	v_mfma_f32_16x16x32_bf16 v[74:77], v[214:217], v[90:93], v[74:77]
	ds_read_b64_tr_b16 v[214:215], v140 offset:8192
	ds_read_b64_tr_b16 v[216:217], v148 offset:8192
	s_waitcnt lgkmcnt(8)
	v_mfma_f32_16x16x32_bf16 v[78:81], v[218:221], v[90:93], v[78:81]
	ds_read_b64_tr_b16 v[218:219], v141 offset:8192
	ds_read_b64_tr_b16 v[220:221], v149 offset:8192
	s_waitcnt lgkmcnt(8)
	v_mfma_f32_16x16x32_bf16 v[82:85], v[222:225], v[90:93], v[82:85]
	ds_read_b64_tr_b16 v[222:223], v142 offset:8192
	ds_read_b64_tr_b16 v[224:225], v150 offset:8192
	s_waitcnt lgkmcnt(8)
	v_mfma_f32_16x16x32_bf16 v[86:89], v[226:229], v[90:93], v[86:89]
	ds_read_b64_tr_b16 v[226:227], v143 offset:8192
	ds_read_b64_tr_b16 v[228:229], v151 offset:8192
	s_waitcnt lgkmcnt(8)
	v_mfma_f32_16x16x32_bf16 v[30:33], v[210:213], v[90:93], v[30:33]
	ds_read_b64_tr_b16 v[210:211], v144 offset:8192
	ds_read_b64_tr_b16 v[212:213], v152 offset:8192
	s_waitcnt lgkmcnt(8)
	v_mfma_f32_16x16x32_bf16 v[26:29], v[214:217], v[242:245], v[26:29]
	ds_read_b64_tr_b16 v[214:215], v145 offset:8192
	ds_read_b64_tr_b16 v[216:217], v153 offset:8192
	s_waitcnt lgkmcnt(8)
	v_mfma_f32_16x16x32_bf16 v[34:37], v[218:221], v[242:245], v[34:37]
	ds_read_b64_tr_b16 v[218:219], v146 offset:8192
	ds_read_b64_tr_b16 v[220:221], v154 offset:8192
	s_waitcnt lgkmcnt(8)
	v_mfma_f32_16x16x32_bf16 v[38:41], v[222:225], v[242:245], v[38:41]
	ds_read_b64_tr_b16 v[222:223], v147 offset:8192
	ds_read_b64_tr_b16 v[224:225], v155 offset:8192
	s_waitcnt lgkmcnt(8)
	v_mfma_f32_16x16x32_bf16 v[42:45], v[226:229], v[242:245], v[42:45]
	ds_read_b64_tr_b16 v[226:227], v140 offset:24576
	ds_read_b64_tr_b16 v[228:229], v148 offset:24576
	s_waitcnt lgkmcnt(8)
	v_mfma_f32_16x16x32_bf16 v[46:49], v[210:213], v[242:245], v[46:49]
	ds_read_b64_tr_b16 v[210:211], v141 offset:24576
	ds_read_b64_tr_b16 v[212:213], v149 offset:24576
	s_waitcnt lgkmcnt(8)
	v_mfma_f32_16x16x32_bf16 v[50:53], v[214:217], v[242:245], v[50:53]
	ds_read_b64_tr_b16 v[214:215], v142 offset:24576
	ds_read_b64_tr_b16 v[216:217], v150 offset:24576
	s_waitcnt lgkmcnt(8)
	v_mfma_f32_16x16x32_bf16 v[54:57], v[218:221], v[242:245], v[54:57]
	ds_read_b64_tr_b16 v[218:219], v143 offset:24576
	ds_read_b64_tr_b16 v[220:221], v151 offset:24576
	s_waitcnt lgkmcnt(8)
	v_mfma_f32_16x16x32_bf16 v[58:61], v[222:225], v[242:245], v[58:61]
	ds_read_b64_tr_b16 v[222:223], v144 offset:24576
	ds_read_b64_tr_b16 v[224:225], v152 offset:24576
	s_waitcnt lgkmcnt(8)
	v_mfma_f32_16x16x32_bf16 v[62:65], v[226:229], v[242:245], v[62:65]
	ds_read_b64_tr_b16 v[226:227], v145 offset:24576
	ds_read_b64_tr_b16 v[228:229], v153 offset:24576
	s_waitcnt lgkmcnt(8)
	v_mfma_f32_16x16x32_bf16 v[66:69], v[210:213], v[242:245], v[66:69]
	ds_read_b64_tr_b16 v[210:211], v146 offset:24576
	ds_read_b64_tr_b16 v[212:213], v154 offset:24576
	s_waitcnt lgkmcnt(8)
	v_mfma_f32_16x16x32_bf16 v[70:73], v[214:217], v[242:245], v[70:73]
	ds_read_b64_tr_b16 v[214:215], v147 offset:24576
	ds_read_b64_tr_b16 v[216:217], v155 offset:24576
	s_waitcnt lgkmcnt(8)
	v_mfma_f32_16x16x32_bf16 v[74:77], v[218:221], v[242:245], v[74:77]
	s_waitcnt lgkmcnt(6)
	v_mfma_f32_16x16x32_bf16 v[78:81], v[222:225], v[242:245], v[78:81]
	s_waitcnt lgkmcnt(4)
	v_mfma_f32_16x16x32_bf16 v[82:85], v[226:229], v[242:245], v[82:85]
	s_waitcnt lgkmcnt(2)
	v_mfma_f32_16x16x32_bf16 v[86:89], v[210:213], v[242:245], v[86:89]
	s_waitcnt lgkmcnt(0)
	s_barrier
; __device__ __forceinline__ f32x4 mma16(bf16x8 a, bf16x8 b, f32x4 c) { return __builtin_amdgcn_mfma_f32_16x16x32_bf16(a, b, c, 0, 0, 0); }
; __device__ __forceinline__ void ma_ret_item(const Params& p, ldsp lds, int item) {
;     ...
;     for (int j = 0; j < 4; ++j) { const size_t rowj = (size_t)b * 2048 + (sc * 4 + j) * 64;
;         st_T<256>(KTt, 72, kr, wave, lane); st_T<128>(VTt, 72, vr, wave, lane);
;         __syncthreads();
;         if (j < 3) { const size_t rown = rowj + 64; ld_T<256>(kr, Pb + rown * NO + O_K + h * 256, NO, wave, lane); ld_T<128>(vr, Pb + rown * NO + O_V + h * 512 + es * 128, NO, wave, lane); }
; #pragma unroll
;         for (int ks = 0; ks < 2; ++ks) { const bf16x8 bf = ldfrag(VTt, (16 * wave + l15) * 72 + 32 * ks + 8 * q4);
; #pragma unroll
;             for (int i = 0; i < 16; ++i) acc[i] = mma16(ldfrag(KTt, (16 * i + l15) * 72 + 32 * ks + 8 * q4), bf, acc[i]); }
;         __syncthreads(); }
	v_mfma_f32_16x16x32_bf16 v[30:33], v[214:217], v[242:245], v[30:33]
	s_waitcnt vmcnt(11)
	ds_write_b128 v172, v[22:25]
	s_waitcnt vmcnt(10)
	ds_write_b128 v173, v[18:21]
	s_waitcnt vmcnt(9)
	ds_write_b128 v172, v[12:15] offset:16384
	s_waitcnt vmcnt(8)
	ds_write_b128 v173, v[4:7] offset:16384
	s_waitcnt vmcnt(7)
	ds_write_b128 v174, v[8:11]
	s_waitcnt vmcnt(6)
	ds_write_b128 v175, v[0:3]
	s_waitcnt lgkmcnt(0)
	s_barrier
	ds_read_b64_tr_b16 v[90:91], v156
	ds_read_b64_tr_b16 v[92:93], v157
	ds_read_b64_tr_b16 v[242:243], v156 offset:8192
	ds_read_b64_tr_b16 v[244:245], v157 offset:8192
	ds_read_b64_tr_b16 v[210:211], v140
	ds_read_b64_tr_b16 v[212:213], v148
	ds_read_b64_tr_b16 v[214:215], v141
	ds_read_b64_tr_b16 v[216:217], v149
	ds_read_b64_tr_b16 v[218:219], v142
	ds_read_b64_tr_b16 v[220:221], v150
	ds_read_b64_tr_b16 v[222:223], v143
	ds_read_b64_tr_b16 v[224:225], v151
	ds_read_b64_tr_b16 v[226:227], v144
	ds_read_b64_tr_b16 v[228:229], v152
	s_waitcnt lgkmcnt(8)
	v_mfma_f32_16x16x32_bf16 v[26:29], v[210:213], v[90:93], v[26:29]
	ds_read_b64_tr_b16 v[210:211], v145
	ds_read_b64_tr_b16 v[212:213], v153
	s_waitcnt lgkmcnt(8)
	v_mfma_f32_16x16x32_bf16 v[34:37], v[214:217], v[90:93], v[34:37]
	ds_read_b64_tr_b16 v[214:215], v146
	ds_read_b64_tr_b16 v[216:217], v154
	s_waitcnt lgkmcnt(8)
	v_mfma_f32_16x16x32_bf16 v[38:41], v[218:221], v[90:93], v[38:41]
	ds_read_b64_tr_b16 v[218:219], v147
	ds_read_b64_tr_b16 v[220:221], v155
	s_waitcnt lgkmcnt(8)
	v_mfma_f32_16x16x32_bf16 v[42:45], v[222:225], v[90:93], v[42:45]
	ds_read_b64_tr_b16 v[222:223], v140 offset:16384
	ds_read_b64_tr_b16 v[224:225], v148 offset:16384
	s_waitcnt lgkmcnt(8)
	v_mfma_f32_16x16x32_bf16 v[46:49], v[226:229], v[90:93], v[46:49]
	ds_read_b64_tr_b16 v[226:227], v141 offset:16384
	ds_read_b64_tr_b16 v[228:229], v149 offset:16384
	s_waitcnt lgkmcnt(8)
	v_mfma_f32_16x16x32_bf16 v[50:53], v[210:213], v[90:93], v[50:53]
	ds_read_b64_tr_b16 v[210:211], v142 offset:16384
	ds_read_b64_tr_b16 v[212:213], v150 offset:16384
	s_waitcnt lgkmcnt(8)
	v_mfma_f32_16x16x32_bf16 v[54:57], v[214:217], v[90:93], v[54:57]
	ds_read_b64_tr_b16 v[214:215], v143 offset:16384
	ds_read_b64_tr_b16 v[216:217], v151 offset:16384
	s_waitcnt lgkmcnt(8)
	v_mfma_f32_16x16x32_bf16 v[58:61], v[218:221], v[90:93], v[58:61]
	ds_read_b64_tr_b16 v[218:219], v144 offset:16384
	ds_read_b64_tr_b16 v[220:221], v152 offset:16384
	s_waitcnt lgkmcnt(8)
	v_mfma_f32_16x16x32_bf16 v[62:65], v[222:225], v[90:93], v[62:65]
	ds_read_b64_tr_b16 v[222:223], v145 offset:16384
	ds_read_b64_tr_b16 v[224:225], v153 offset:16384
	s_waitcnt lgkmcnt(8)
	v_mfma_f32_16x16x32_bf16 v[66:69], v[226:229], v[90:93], v[66:69]
	ds_read_b64_tr_b16 v[226:227], v146 offset:16384
	ds_read_b64_tr_b16 v[228:229], v154 offset:16384
	s_waitcnt lgkmcnt(8)
	v_mfma_f32_16x16x32_bf16 v[70:73], v[210:213], v[90:93], v[70:73]
	ds_read_b64_tr_b16 v[210:211], v147 offset:16384
	ds_read_b64_tr_b16 v[212:213], v155 offset:16384
	s_waitcnt lgkmcnt(8)
	v_mfma_f32_16x16x32_bf16 v[74:77], v[214:217], v[90:93], v[74:77]
	ds_read_b64_tr_b16 v[214:215], v140 offset:8192
	ds_read_b64_tr_b16 v[216:217], v148 offset:8192
	s_waitcnt lgkmcnt(8)
	v_mfma_f32_16x16x32_bf16 v[78:81], v[218:221], v[90:93], v[78:81]
	ds_read_b64_tr_b16 v[218:219], v141 offset:8192
	ds_read_b64_tr_b16 v[220:221], v149 offset:8192
	s_waitcnt lgkmcnt(8)
	v_mfma_f32_16x16x32_bf16 v[82:85], v[222:225], v[90:93], v[82:85]
	ds_read_b64_tr_b16 v[222:223], v142 offset:8192
	ds_read_b64_tr_b16 v[224:225], v150 offset:8192
	s_waitcnt lgkmcnt(8)
	v_mfma_f32_16x16x32_bf16 v[86:89], v[226:229], v[90:93], v[86:89]
	ds_read_b64_tr_b16 v[226:227], v143 offset:8192
	ds_read_b64_tr_b16 v[228:229], v151 offset:8192
	s_waitcnt lgkmcnt(8)
	v_mfma_f32_16x16x32_bf16 v[30:33], v[210:213], v[90:93], v[30:33]
	ds_read_b64_tr_b16 v[210:211], v144 offset:8192
	ds_read_b64_tr_b16 v[212:213], v152 offset:8192
	s_waitcnt lgkmcnt(8)
	v_mfma_f32_16x16x32_bf16 v[26:29], v[214:217], v[242:245], v[26:29]
	ds_read_b64_tr_b16 v[214:215], v145 offset:8192
	ds_read_b64_tr_b16 v[216:217], v153 offset:8192
	s_waitcnt lgkmcnt(8)
	v_mfma_f32_16x16x32_bf16 v[34:37], v[218:221], v[242:245], v[34:37]
	ds_read_b64_tr_b16 v[218:219], v146 offset:8192
	ds_read_b64_tr_b16 v[220:221], v154 offset:8192
	s_waitcnt lgkmcnt(8)
	v_mfma_f32_16x16x32_bf16 v[38:41], v[222:225], v[242:245], v[38:41]
	ds_read_b64_tr_b16 v[222:223], v147 offset:8192
	ds_read_b64_tr_b16 v[224:225], v155 offset:8192
	s_waitcnt lgkmcnt(8)
	v_mfma_f32_16x16x32_bf16 v[42:45], v[226:229], v[242:245], v[42:45]
	ds_read_b64_tr_b16 v[226:227], v140 offset:24576
	ds_read_b64_tr_b16 v[228:229], v148 offset:24576
	s_waitcnt lgkmcnt(8)
	v_mfma_f32_16x16x32_bf16 v[46:49], v[210:213], v[242:245], v[46:49]
	ds_read_b64_tr_b16 v[210:211], v141 offset:24576
	ds_read_b64_tr_b16 v[212:213], v149 offset:24576
	s_waitcnt lgkmcnt(8)
	v_mfma_f32_16x16x32_bf16 v[50:53], v[214:217], v[242:245], v[50:53]
	ds_read_b64_tr_b16 v[214:215], v142 offset:24576
	ds_read_b64_tr_b16 v[216:217], v150 offset:24576
	s_waitcnt lgkmcnt(8)
	v_mfma_f32_16x16x32_bf16 v[54:57], v[218:221], v[242:245], v[54:57]
	ds_read_b64_tr_b16 v[218:219], v143 offset:24576
	ds_read_b64_tr_b16 v[220:221], v151 offset:24576
	s_waitcnt lgkmcnt(8)
	v_mfma_f32_16x16x32_bf16 v[58:61], v[222:225], v[242:245], v[58:61]
	ds_read_b64_tr_b16 v[222:223], v144 offset:24576
	ds_read_b64_tr_b16 v[224:225], v152 offset:24576
	s_waitcnt lgkmcnt(8)
	v_mfma_f32_16x16x32_bf16 v[62:65], v[226:229], v[242:245], v[62:65]
	ds_read_b64_tr_b16 v[226:227], v145 offset:24576
	ds_read_b64_tr_b16 v[228:229], v153 offset:24576
	s_waitcnt lgkmcnt(8)
	v_mfma_f32_16x16x32_bf16 v[66:69], v[210:213], v[242:245], v[66:69]
	ds_read_b64_tr_b16 v[210:211], v146 offset:24576
	ds_read_b64_tr_b16 v[212:213], v154 offset:24576
	s_waitcnt lgkmcnt(8)
	v_mfma_f32_16x16x32_bf16 v[70:73], v[214:217], v[242:245], v[70:73]
	ds_read_b64_tr_b16 v[214:215], v147 offset:24576
	ds_read_b64_tr_b16 v[216:217], v155 offset:24576
	s_waitcnt lgkmcnt(8)
	v_mfma_f32_16x16x32_bf16 v[74:77], v[218:221], v[242:245], v[74:77]
	s_waitcnt lgkmcnt(6)
	v_mfma_f32_16x16x32_bf16 v[78:81], v[222:225], v[242:245], v[78:81]
	s_waitcnt lgkmcnt(4)
	v_mfma_f32_16x16x32_bf16 v[82:85], v[226:229], v[242:245], v[82:85]
	s_waitcnt lgkmcnt(2)
	v_mfma_f32_16x16x32_bf16 v[86:89], v[210:213], v[242:245], v[86:89]
	s_waitcnt lgkmcnt(0)
	s_barrier
; __device__ __forceinline__ f32x4 mma16(bf16x8 a, bf16x8 b, f32x4 c) { return __builtin_amdgcn_mfma_f32_16x16x32_bf16(a, b, c, 0, 0, 0); }
; __device__ __forceinline__ void ma_ret_item(const Params& p, ldsp lds, int item) {
;     ...
;         st_T<256>(KTt, 72, kr, wave, lane); st_T<128>(VTt, 72, vr, wave, lane);
;         __syncthreads();
;         if (j < 3) { const size_t rown = rowj + 64; ld_T<256>(kr, Pb + rown * NO + O_K + h * 256, NO, wave, lane); ld_T<128>(vr, Pb + rown * NO + O_V + h * 512 + es * 128, NO, wave, lane); }
; #pragma unroll
;         for (int ks = 0; ks < 2; ++ks) { const bf16x8 bf = ldfrag(VTt, (16 * wave + l15) * 72 + 32 * ks + 8 * q4);
; #pragma unroll
;             for (int i = 0; i < 16; ++i) acc[i] = mma16(ldfrag(KTt, (16 * i + l15) * 72 + 32 * ks + 8 * q4), bf, acc[i]); }
;         __syncthreads(); }
	v_mfma_f32_16x16x32_bf16 v[30:33], v[214:217], v[242:245], v[30:33]
	s_waitcnt vmcnt(5)
	ds_write_b16 v100, v186
	ds_write_b16_d16_hi v100, v186 offset:144
	ds_write_b16 v100, v187 offset:288
	ds_write_b16_d16_hi v100, v187 offset:432
	ds_write_b16 v100, v188 offset:576
	ds_write_b16_d16_hi v100, v188 offset:720
	ds_write_b16 v100, v189 offset:864
	ds_write_b16_d16_hi v100, v189 offset:1008
	s_waitcnt vmcnt(4)
	ds_write_b16 v100, v190 offset:9216
	ds_write_b16_d16_hi v100, v190 offset:9360
	ds_write_b16 v100, v191 offset:9504
	ds_write_b16_d16_hi v100, v191 offset:9648
	ds_write_b16 v100, v192 offset:9792
	ds_write_b16_d16_hi v100, v192 offset:9936
	ds_write_b16 v100, v193 offset:10080
	ds_write_b16_d16_hi v100, v193 offset:10224
	s_waitcnt vmcnt(3)
	ds_write_b16 v100, v194 offset:18432
	ds_write_b16_d16_hi v100, v194 offset:18576
	ds_write_b16 v100, v195 offset:18720
	ds_write_b16_d16_hi v100, v195 offset:18864
	ds_write_b16 v100, v196 offset:19008
	ds_write_b16_d16_hi v100, v196 offset:19152
	ds_write_b16 v100, v197 offset:19296
	ds_write_b16_d16_hi v100, v197 offset:19440
	s_waitcnt vmcnt(2)
	ds_write_b16 v100, v206 offset:27648
	ds_write_b16_d16_hi v100, v206 offset:27792
	ds_write_b16 v100, v207 offset:27936
	ds_write_b16_d16_hi v100, v207 offset:28080
	ds_write_b16 v100, v208 offset:28224
	ds_write_b16_d16_hi v100, v208 offset:28368
	ds_write_b16 v100, v209 offset:28512
	ds_write_b16_d16_hi v100, v209 offset:28656
	s_waitcnt vmcnt(1)
	ds_write_b16 v100, v230 offset:36864
	ds_write_b16_d16_hi v100, v230 offset:37008
	ds_write_b16 v100, v231 offset:37152
	ds_write_b16_d16_hi v100, v231 offset:37296
	ds_write_b16 v100, v232 offset:37440
	ds_write_b16_d16_hi v100, v232 offset:37584
	ds_write_b16 v100, v233 offset:37728
	ds_write_b16_d16_hi v100, v233 offset:37872
	s_waitcnt vmcnt(0)
	ds_write_b16 v100, v234 offset:46080
	ds_write_b16_d16_hi v100, v234 offset:46224
	ds_write_b16 v100, v235 offset:46368
	ds_write_b16_d16_hi v100, v235 offset:46512
	ds_write_b16 v100, v236 offset:46656
	ds_write_b16_d16_hi v100, v236 offset:46800
	ds_write_b16 v100, v237 offset:46944
	ds_write_b16_d16_hi v100, v237 offset:47088
	s_waitcnt lgkmcnt(0)
	s_barrier
	ds_read_b128 v[0:3], v132
	ds_read_b128 v[4:7], v130 offset:36864
	ds_read_b128 v[8:11], v131
	ds_read_b128 v[12:15], v130 offset:36928
	ds_read_b128 v[18:21], v129
	ds_read_b128 v[22:25], v128
	s_waitcnt lgkmcnt(4)
	v_mfma_f32_16x16x32_bf16 v[0:3], v[0:3], v[4:7], v[26:29]
	s_ashr_i32 s1, s0, 31
	v_readlane_b32 s10, v255, 9
	s_lshl_b64 s[0:1], s[0:1], 12
	s_waitcnt lgkmcnt(3)
	v_mfma_f32_16x16x32_bf16 v[8:11], v[8:11], v[4:7], v[34:37]
	ds_read_b128 v[26:29], v127
	v_readlane_b32 s11, v255, 10
	s_or_b64 s[0:1], s[0:1], s[10:11]
	s_waitcnt lgkmcnt(2)
	v_mfma_f32_16x16x32_bf16 v[18:21], v[18:21], v[4:7], v[38:41]
	ds_read_b128 v[34:37], v126
	s_ashr_i32 s9, s8, 31
	s_add_i32 s12, s12, 1
	s_waitcnt lgkmcnt(2)
	v_mfma_f32_16x16x32_bf16 v[22:25], v[22:25], v[4:7], v[42:45]
	ds_read_b128 v[38:41], v125
	s_cmp_eq_u32 s12, 4
	s_nop 0
	ds_read_b128 v[42:45], v124
	s_waitcnt lgkmcnt(3)
	v_mfma_f32_16x16x32_bf16 v[26:29], v[26:29], v[4:7], v[46:49]
	s_waitcnt lgkmcnt(2)
	v_mfma_f32_16x16x32_bf16 v[34:37], v[34:37], v[4:7], v[50:53]
	s_nop 0
	ds_read_b128 v[46:49], v123
	s_nop 0
	ds_read_b128 v[50:53], v122
	s_waitcnt lgkmcnt(3)
	v_mfma_f32_16x16x32_bf16 v[38:41], v[38:41], v[4:7], v[54:57]
	s_waitcnt lgkmcnt(2)
	v_mfma_f32_16x16x32_bf16 v[42:45], v[42:45], v[4:7], v[58:61]
	s_nop 0
	ds_read_b128 v[54:57], v121
	s_nop 0
	ds_read_b128 v[58:61], v120
	s_waitcnt lgkmcnt(3)
	v_mfma_f32_16x16x32_bf16 v[46:49], v[46:49], v[4:7], v[62:65]
	s_waitcnt lgkmcnt(2)
	v_mfma_f32_16x16x32_bf16 v[50:53], v[50:53], v[4:7], v[66:69]
	s_nop 0
	ds_read_b128 v[62:65], v119
	s_nop 0
	ds_read_b128 v[66:69], v118
	s_waitcnt lgkmcnt(3)
	v_mfma_f32_16x16x32_bf16 v[54:57], v[54:57], v[4:7], v[70:73]
	s_waitcnt lgkmcnt(2)
	v_mfma_f32_16x16x32_bf16 v[58:61], v[58:61], v[4:7], v[74:77]
	s_nop 0
	ds_read_b128 v[70:73], v117
	s_nop 0
	ds_read_b128 v[74:77], v116
	s_waitcnt lgkmcnt(3)
	v_mfma_f32_16x16x32_bf16 v[62:65], v[62:65], v[4:7], v[78:81]
	s_waitcnt lgkmcnt(2)
	v_mfma_f32_16x16x32_bf16 v[66:69], v[66:69], v[4:7], v[82:85]
	s_nop 0
	ds_read_b128 v[78:81], v115
	s_waitcnt lgkmcnt(2)
	v_mfma_f32_16x16x32_bf16 v[70:73], v[70:73], v[4:7], v[86:89]
	s_waitcnt lgkmcnt(1)
	v_mfma_f32_16x16x32_bf16 v[4:7], v[74:77], v[4:7], v[30:33]
	ds_read_b128 v[74:77], v113
	s_nop 1
	ds_read_b128 v[30:33], v114
	s_waitcnt lgkmcnt(0)
	v_mfma_f32_16x16x32_bf16 v[8:11], v[30:33], v[12:15], v[8:11]
	ds_read_b128 v[30:33], v112
	v_mfma_f32_16x16x32_bf16 v[18:21], v[74:77], v[12:15], v[18:21]
	ds_read_b128 v[74:77], v111
	s_waitcnt lgkmcnt(1)
	v_mfma_f32_16x16x32_bf16 v[22:25], v[30:33], v[12:15], v[22:25]
	ds_read_b128 v[30:33], v110
	s_waitcnt lgkmcnt(1)
	v_mfma_f32_16x16x32_bf16 v[26:29], v[74:77], v[12:15], v[26:29]
	ds_read_b128 v[74:77], v109
	s_waitcnt lgkmcnt(1)
	v_mfma_f32_16x16x32_bf16 v[30:33], v[30:33], v[12:15], v[34:37]
	s_nop 2
	ds_read_b128 v[34:37], v108
	s_waitcnt lgkmcnt(1)
	v_mfma_f32_16x16x32_bf16 v[38:41], v[74:77], v[12:15], v[38:41]
	ds_read_b128 v[74:77], v107
	s_waitcnt lgkmcnt(1)
	v_mfma_f32_16x16x32_bf16 v[34:37], v[34:37], v[12:15], v[42:45]
	s_nop 2
	ds_read_b128 v[42:45], v106
	s_waitcnt lgkmcnt(1)
	v_mfma_f32_16x16x32_bf16 v[46:49], v[74:77], v[12:15], v[46:49]
	ds_read_b128 v[74:77], v105
	s_waitcnt lgkmcnt(1)
	v_mfma_f32_16x16x32_bf16 v[42:45], v[42:45], v[12:15], v[50:53]
	s_nop 2
	ds_read_b128 v[50:53], v104
	v_mfma_f32_16x16x32_bf16 v[0:3], v[78:81], v[12:15], v[0:3]
	s_waitcnt lgkmcnt(1)
	v_mfma_f32_16x16x32_bf16 v[54:57], v[74:77], v[12:15], v[54:57]
	ds_read_b128 v[74:77], v103
	ds_read_b128 v[78:81], v102
	s_waitcnt lgkmcnt(2)
	v_mfma_f32_16x16x32_bf16 v[50:53], v[50:53], v[12:15], v[58:61]
	s_nop 2
	ds_read_b128 v[58:61], v101
	ds_read_b128 v[82:85], v16
	s_waitcnt lgkmcnt(0)
	s_barrier
; __device__ __forceinline__ unsigned pk2(float lo, float hi) { return pg8::cvt_pk_bf16(lo, hi); }
; __device__ __forceinline__ f32x4 mma16(bf16x8 a, bf16x8 b, f32x4 c) { return __builtin_amdgcn_mfma_f32_16x16x32_bf16(a, b, c, 0, 0, 0); }
; __device__ __forceinline__ void ma_ret_item(const Params& p, ldsp lds, int item) {
;     ...
;             for (int i = 0; i < 16; ++i) acc[i] = mma16(ldfrag(KTt, (16 * i + l15) * 72 + 32 * ks + 8 * q4), bf, acc[i]); }
;         __syncthreads(); }
;     bf16_t* HL = (bf16_t*)(p.ws + WS_HL) + (((size_t)bh * 8 + sc) * 512 + es * 128 + 16 * wave + l15) * 256;
; #pragma unroll
;     for (int i = 0; i < 16; ++i) { u32x2 w; w.x = pk2(acc[i][0], acc[i][1]); w.y = pk2(acc[i][2], acc[i][3]); *(u32x2*)(HL + 16 * i + 4 * q4) = w; }
; __global__ void __launch_bounds__(NTHREADS, 2) fwd_megakernel(Params p) {
;     ...
;                 if (G == 256) { const int xq = bid & 7, yq = bid >> 3;
;                     for (int k = 0; k < 4; ++k) { const int q = k * 64 + xq * 8 + (yq >> 2); ma_ret_item(p, lds, q * 4 + (yq & 3)); } }
	v_mfma_f32_16x16x32_bf16 v[58:61], v[58:61], v[12:15], v[70:73]
	v_cvt_pk_bf16_f32 v0, v0, v1
	v_cvt_pk_bf16_f32 v1, v2, v3
	v_mfma_f32_16x16x32_bf16 v[62:65], v[74:77], v[12:15], v[62:65]
	s_nop 1
	v_or_b32_e32 v70, s0, v95
	v_mov_b32_e32 v71, s1
	v_lshl_add_u64 v[70:71], v[70:71], 0, s[8:9]
	v_readlane_b32 s0, v253, 34
	v_mfma_f32_16x16x32_bf16 v[66:69], v[78:81], v[12:15], v[66:69]
	v_readlane_b32 s1, v253, 35
	v_mov_b32_e32 v95, v17
	v_mfma_f32_16x16x32_bf16 v[4:7], v[82:85], v[12:15], v[4:7]
	v_lshlrev_b64 v[12:13], 9, v[70:71]
	v_lshl_add_u64 v[12:13], s[0:1], 0, v[12:13]
	v_lshl_add_u64 v[12:13], v[12:13], 0, v[94:95]
	global_store_dwordx2 v[12:13], v[0:1], off
	v_cvt_pk_bf16_f32 v0, v8, v9
	v_cvt_pk_bf16_f32 v1, v10, v11
	global_store_dwordx2 v[12:13], v[0:1], off offset:32
	v_cvt_pk_bf16_f32 v0, v18, v19
	v_cvt_pk_bf16_f32 v1, v20, v21
	global_store_dwordx2 v[12:13], v[0:1], off offset:64
	v_cvt_pk_bf16_f32 v0, v22, v23
	v_cvt_pk_bf16_f32 v1, v24, v25
	global_store_dwordx2 v[12:13], v[0:1], off offset:96
	v_cvt_pk_bf16_f32 v0, v26, v27
	v_cvt_pk_bf16_f32 v1, v28, v29
	global_store_dwordx2 v[12:13], v[0:1], off offset:128
	v_cvt_pk_bf16_f32 v0, v30, v31
	v_cvt_pk_bf16_f32 v1, v32, v33
	global_store_dwordx2 v[12:13], v[0:1], off offset:160
	v_cvt_pk_bf16_f32 v0, v38, v39
	v_cvt_pk_bf16_f32 v1, v40, v41
	global_store_dwordx2 v[12:13], v[0:1], off offset:192
	v_cvt_pk_bf16_f32 v0, v34, v35
	v_cvt_pk_bf16_f32 v1, v36, v37
	global_store_dwordx2 v[12:13], v[0:1], off offset:224
	v_cvt_pk_bf16_f32 v0, v46, v47
	v_cvt_pk_bf16_f32 v1, v48, v49
	global_store_dwordx2 v[12:13], v[0:1], off offset:256
	v_cvt_pk_bf16_f32 v0, v42, v43
	v_cvt_pk_bf16_f32 v1, v44, v45
	global_store_dwordx2 v[12:13], v[0:1], off offset:288
	v_cvt_pk_bf16_f32 v0, v54, v55
	v_cvt_pk_bf16_f32 v1, v56, v57
	global_store_dwordx2 v[12:13], v[0:1], off offset:320
	v_cvt_pk_bf16_f32 v0, v50, v51
	v_cvt_pk_bf16_f32 v1, v52, v53
	global_store_dwordx2 v[12:13], v[0:1], off offset:352
	v_cvt_pk_bf16_f32 v0, v62, v63
	v_cvt_pk_bf16_f32 v1, v64, v65
	global_store_dwordx2 v[12:13], v[0:1], off offset:384
	v_cvt_pk_bf16_f32 v0, v66, v67
	v_cvt_pk_bf16_f32 v1, v68, v69
	global_store_dwordx2 v[12:13], v[0:1], off offset:416
	v_cvt_pk_bf16_f32 v0, v58, v59
	v_cvt_pk_bf16_f32 v1, v60, v61
	global_store_dwordx2 v[12:13], v[0:1], off offset:448
	v_cvt_pk_bf16_f32 v0, v4, v5
	v_cvt_pk_bf16_f32 v1, v6, v7
	global_store_dwordx2 v[12:13], v[0:1], off offset:480
	s_cbranch_scc0 .LBB0_677
